# P3 work queue: the next item id is requested (atomic) at the start of the current item instead of between items
# baseline (speedup 1.0000x reference)
.LBB0_439:
	s_or_b64 exec, exec, s[4:5]
	s_add_u32 s20, s94, 0x8008000
	s_addc_u32 s21, s95, 0
	s_add_u32 s24, s94, 0x13288000
	s_addc_u32 s25, s95, 0
	s_add_u32 s33, s94, 0x1c708000
	s_addc_u32 s62, s95, 0
	s_add_u32 s63, s94, 0x1c508000
	s_addc_u32 s52, s95, 0
	s_add_u32 s53, s94, 0x19f08000
	s_load_dwordx16 s[36:51], s[0:1], 0xc0
	s_addc_u32 s54, s95, 0
	s_add_u32 s55, s94, 0x1b008000
	v_and_b32_e32 v2, 32, v204
	s_addc_u32 s60, s95, 0
	v_cmp_eq_u32_e64 s[4:5], 0, v2
	v_and_b32_e32 v2, 63, v204
	s_add_u32 s26, s94, 0x4008000
	v_mov_b32_e32 v1, 0
	v_cmp_eq_u32_e64 s[6:7], 0, v0
	v_lshlrev_b32_e32 v0, 6, v2
	s_waitcnt lgkmcnt(0)
	s_mov_b64 s[28:29], s[48:49]
	s_addc_u32 s27, s95, 0
	v_lshl_add_u64 v[172:173], s[28:29], 0, v[0:1]
	s_add_u32 s28, s94, 0x1cb08000
	s_mov_b64 s[30:31], s[50:51]
	s_addc_u32 s29, s95, 0
	s_waitcnt vmcnt(63) expcnt(7) lgkmcnt(15)
	s_barrier
	ds_read_b32 v166, v1 offset:20
	v_lshl_add_u64 v[170:171], s[30:31], 0, v[0:1]
	s_add_u32 s30, s94, 0x8000
	s_addc_u32 s31, s95, 0
	s_add_u32 s34, s94, 0x1cb18000
	s_addc_u32 s35, s95, 0
	s_add_u32 s61, s94, 0x8255000
	s_mov_b32 s19, 0
	v_lshrrev_b32_e32 v180, 6, v204
	v_cmp_eq_u32_e64 s[8:9], 0, v2
	v_lshlrev_b32_e32 v168, 3, v2
	v_mov_b32_e32 v169, v1
	s_waitcnt lgkmcnt(0)
	v_mov_b32_e32 v167, v166
	s_addc_u32 s64, s95, 0
	s_movk_i32 s65, 0x5400
	s_movk_i32 s66, 0x110
	s_mov_b64 s[40:41], 0x1000
	s_movk_i32 s67, 0x1000
	s_mov_b32 s68, 0x54000
	s_mov_b32 s69, 0x55000
	s_mov_b32 s70, 0xa8000
	s_mov_b32 s71, 0xa9000
	s_mov_b32 s72, 0xfc000
	s_mov_b32 s73, 0xfd000
	s_movk_i32 s74, 0x120
	s_movk_i32 s75, 0x80
	v_mov_b32_e32 v181, 0x358637bd
	s_mov_b32 s78, 0x800000
	s_mov_b32 s23, 0x13288000
	s_movk_i32 s80, 0x2000
	s_movk_i32 s81, 0x4000
	s_movk_i32 s86, 0x6000
	s_mov_b32 s87, 0x8000
	s_mov_b32 s88, 0xa000
	s_mov_b32 s89, 0xc000
	s_mov_b32 s90, 0xe000
	s_mov_b32 s91, 0x10000
	s_mov_b32 s79, 0x18000
	s_mov_b32 s3, 0xc0e00000
	v_mov_b32_e32 v182, 0x5400
	v_mov_b32_e32 v183, 0x40e00000
	v_mov_b32_e32 v242, 1
	s_and_saveexec_b64 s[10:11], s[56:57]
	global_atomic_add v243, v1, v242, s[94:95] sc0
	s_or_b64 exec, exec, s[10:11]
	s_branch .LBB0_442

.LBB0_442:
	s_barrier
	s_and_saveexec_b64 s[10:11], s[56:57]
	s_cbranch_execz .LBB0_446
	s_waitcnt vmcnt(0)
	ds_write_b32 v1, v243 offset:16
	global_atomic_add v243, v1, v242, s[94:95] sc0
